# prep waves rewritten by hand: 8-token decay group per iteration, 10-row sliding-window loads through scalar row pointers, shared row differences, one bf16 MFMA batch per group, no loop-carried copies
# speedup vs baseline: 1.1465x; 1.0389x over previous
; DEV int tid_() { int t = threadIdx.x; asm volatile("" : "+v"(t)); return t; }
; __device__ void scan_chain(PRef p, int l, int chain, ScanSm* sm) {
;   int b = chain >> 4, h = (chain >> 1) & 7, d = chain & 1;
;   int tid = tid_(), wave = tid >> 6, lane = tid & 63;
;   f32x4v* xch = (f32x4v*)sm->xch;
;   __syncthreads();
;   if (wave < 2) {
;     xch[(0 * 2 + wave) * 64 + lane] = f32x4v{0.f, 0.f, 0.f, 0.f};
;     xch[(1 * 2 + wave) * 64 + lane] = f32x4v{0.f, 0.f, 0.f, 0.f};
;   }
;   __syncthreads();
;   if (wave < 2) __builtin_amdgcn_s_setprio(3); else __builtin_amdgcn_s_setprio(3);
;     ...
;     PrepConst pc;
;     int hc = h * 64 + lane;
;     pc.cols[0] = hc; pc.cols[1] = 512 + hc; pc.cols[2] = 1024 + hc; pc.cols[3] = 1536 + d * 64 + lane; pc.cols[4] = 1664 + d * 64 + lane;
; #pragma unroll
;     for (int i = 0; i < 5; i++) { pc.mup[i] = p.a_mu_prev[l * 1792 + pc.cols[i]]; pc.mun[i] = p.a_mu_next[l * 1792 + pc.cols[i]]; }
;     pc.w0v = p.a_w0[l * 1024 + d * 512 + hc];
;     pc.a0v = p.a_a0[l * 1024 + d * 512 + hc];
;     pc.kkc = p.a_k_k[l * 512 + hc];
;     pc.kac = p.a_k_a[l * 512 + hc];
;     pc.rkc = p.a_r_k[l * 512 + hc];
;     {
;       const float* wu = p.a_w_up + ((size_t)(l * 2 + d) * 64) * 512 + hc;
;       const float* au = p.a_a_up + ((size_t)(l * 2 + d) * 64) * 512 + hc;
; #pragma unroll
;       for (int r = 0; r < 32; r++) {
;         pc.wu[r] = pack2(wu[(2 * r) * 512], wu[(2 * r + 1) * 512]);
;         pc.au[r] = pack2(au[(2 * r) * 512], au[(2 * r + 1) * 512]);
;       }
;     }
.LBB0_567:
	s_or_b64 exec, exec, s[6:7]
	s_ashr_i32 s28, s56, 4
	s_bfe_u32 s63, s56, 0x30001
	s_and_b32 s62, s56, 1
	s_waitcnt lgkmcnt(0)
	s_barrier
	s_setprio 3
	s_mulk_i32 s28, 0x900
	s_and_saveexec_b64 s[0:1], vcc
	s_xor_b64 s[20:21], exec, s[0:1]
	s_cbranch_execz .LBB0_606
	v_lshl_or_b32 v7, s63, 6, v28
	v_add_u32_e32 v0, s57, v7
	v_ashrrev_i32_e32 v1, 31, v0
	v_lshlrev_b64 v[4:5], 2, v[0:1]
	v_add_u32_e32 v0, 0x400, v0
	v_ashrrev_i32_e32 v1, 31, v0
	v_lshl_or_b32 v6, s62, 6, v28
	v_lshl_add_u64 v[8:9], s[36:37], 0, v[4:5]
	v_lshl_add_u64 v[4:5], s[38:39], 0, v[4:5]
	v_lshlrev_b64 v[0:1], 2, v[0:1]
	global_load_dword v14, v[8:9], off
	global_load_dword v15, v[8:9], off offset:2048
	global_load_dword v16, v[4:5], off
	global_load_dword v17, v[4:5], off offset:2048
	v_lshl_add_u64 v[4:5], s[36:37], 0, v[0:1]
	v_lshl_add_u64 v[0:1], s[38:39], 0, v[0:1]
	v_add_u32_e32 v2, s57, v6
	global_load_dword v19, v[0:1], off
	v_add_u32_e32 v0, 0x600, v2
	v_ashrrev_i32_e32 v1, 31, v0
	v_lshlrev_b64 v[0:1], 2, v[0:1]
	global_load_dword v18, v[4:5], off
	v_lshl_add_u64 v[4:5], s[36:37], 0, v[0:1]
	v_lshl_add_u64 v[0:1], s[38:39], 0, v[0:1]
	global_load_dword v21, v[0:1], off
	v_add_u32_e32 v0, 0x680, v2
	v_ashrrev_i32_e32 v1, 31, v0
	v_lshlrev_b64 v[0:1], 2, v[0:1]
	s_lshl_b32 s0, s62, 9
	global_load_dword v20, v[4:5], off
	v_lshl_add_u64 v[4:5], s[36:37], 0, v[0:1]
	v_lshl_add_u64 v[0:1], s[38:39], 0, v[0:1]
	s_or_b32 s0, s0, s58
	global_load_dword v23, v[0:1], off
	v_or_b32_e32 v0, s0, v7
	v_ashrrev_i32_e32 v1, 31, v0
	v_readlane_b32 s0, v245, 10
	v_lshlrev_b64 v[0:1], 2, v[0:1]
	v_readlane_b32 s1, v245, 11
	global_load_dword v22, v[4:5], off
	v_lshl_add_u64 v[4:5], s[40:41], 0, v[0:1]
	v_lshl_add_u64 v[0:1], s[44:45], 0, v[0:1]
	s_load_dwordx2 s[0:1], s[0:1], 0x80
	global_load_dword v25, v[0:1], off
	v_or_b32_e32 v0, s80, v7
	v_ashrrev_i32_e32 v1, 31, v0
	v_lshlrev_b64 v[0:1], 2, v[0:1]
	global_load_dword v24, v[4:5], off
	v_lshl_add_u64 v[4:5], s[48:49], 0, v[0:1]
	global_load_dword v26, v[4:5], off
	v_lshl_add_u64 v[4:5], s[50:51], 0, v[0:1]
	s_waitcnt lgkmcnt(0)
	v_lshl_add_u64 v[0:1], s[0:1], 0, v[0:1]
	s_or_b32 s0, s62, s61
	s_ashr_i32 s1, s0, 31
	s_lshl_b64 s[0:1], s[0:1], 17
	s_add_u32 s4, s42, s0
	s_addc_u32 s5, s43, s1
	s_add_u32 s0, s46, s0
	v_lshlrev_b32_e32 v2, 2, v7
	s_addc_u32 s1, s47, s1
	global_load_dword v27, v[4:5], off
	global_load_dword v29, v[0:1], off
	s_mov_b64 s[10:11], s[4:5]
	s_mov_b64 s[12:13], s[0:1]
	v_lshlrev_b32_e32 v96, 3, v12
	v_cmp_lt_u32_e64 s[8:9], 33, v12
	v_and_b32_e32 v1, 15, v28
	v_lshrrev_b32_e32 v2, 4, v28
	v_lshl_or_b32 v4, s63, 6, v1
	v_lshlrev_b32_e32 v4, 2, v4
	v_lshl_add_u32 v4, v2, 14, v4
	v_cmp_eq_u32_e32 vcc, 1, v1
	v_lshlrev_b32_e32 v5, 4, v2
	v_lshl_add_u32 v5, v12, 9, v5
	v_cndmask_b32_e64 v1, 0, 1, vcc
	v_lshl_add_u32 v92, v1, 8, v5
	v_lshlrev_b32_e32 v93, 3, v28
	v_lshl_add_u32 v93, v12, 11, v93
	s_add_u32 s14, s10, 0x0
	s_addc_u32 s15, s11, 0
	global_load_dword v98, v4, s[14:15] offset:0
	global_load_dword v99, v4, s[14:15] offset:2048
	global_load_dword v100, v4, s[14:15] offset:64
	global_load_dword v101, v4, s[14:15] offset:2112
	global_load_dword v102, v4, s[14:15] offset:128
	global_load_dword v103, v4, s[14:15] offset:2176
	global_load_dword v104, v4, s[14:15] offset:192
	global_load_dword v105, v4, s[14:15] offset:2240
	s_add_u32 s14, s10, 0x1000
	s_addc_u32 s15, s11, 0
	global_load_dword v106, v4, s[14:15] offset:0
	global_load_dword v107, v4, s[14:15] offset:2048
	global_load_dword v108, v4, s[14:15] offset:64
	global_load_dword v109, v4, s[14:15] offset:2112
	global_load_dword v110, v4, s[14:15] offset:128
	global_load_dword v111, v4, s[14:15] offset:2176
	global_load_dword v112, v4, s[14:15] offset:192
	global_load_dword v113, v4, s[14:15] offset:2240
	s_add_u32 s14, s10, 0x2000
	s_addc_u32 s15, s11, 0
	global_load_dword v114, v4, s[14:15] offset:0
	global_load_dword v115, v4, s[14:15] offset:2048
	global_load_dword v116, v4, s[14:15] offset:64
	global_load_dword v117, v4, s[14:15] offset:2112
	global_load_dword v118, v4, s[14:15] offset:128
	global_load_dword v119, v4, s[14:15] offset:2176
	global_load_dword v120, v4, s[14:15] offset:192
	global_load_dword v121, v4, s[14:15] offset:2240
	s_add_u32 s14, s10, 0x3000
	s_addc_u32 s15, s11, 0
	global_load_dword v122, v4, s[14:15] offset:0
	global_load_dword v123, v4, s[14:15] offset:2048
	global_load_dword v124, v4, s[14:15] offset:64
	global_load_dword v125, v4, s[14:15] offset:2112
	global_load_dword v126, v4, s[14:15] offset:128
	global_load_dword v127, v4, s[14:15] offset:2176
	global_load_dword v128, v4, s[14:15] offset:192
	global_load_dword v129, v4, s[14:15] offset:2240
	s_add_u32 s14, s10, 0x10000
	s_addc_u32 s15, s11, 0
	global_load_dword v130, v4, s[14:15] offset:0
	global_load_dword v131, v4, s[14:15] offset:2048
	global_load_dword v133, v4, s[14:15] offset:64
	global_load_dword v134, v4, s[14:15] offset:2112
	global_load_dword v135, v4, s[14:15] offset:128
	global_load_dword v136, v4, s[14:15] offset:2176
	global_load_dword v137, v4, s[14:15] offset:192
	global_load_dword v138, v4, s[14:15] offset:2240
	s_add_u32 s14, s10, 0x11000
	s_addc_u32 s15, s11, 0
	global_load_dword v139, v4, s[14:15] offset:0
	global_load_dword v140, v4, s[14:15] offset:2048
	global_load_dword v141, v4, s[14:15] offset:64
	global_load_dword v142, v4, s[14:15] offset:2112
	global_load_dword v143, v4, s[14:15] offset:128
	global_load_dword v144, v4, s[14:15] offset:2176
	global_load_dword v145, v4, s[14:15] offset:192
	global_load_dword v146, v4, s[14:15] offset:2240
	s_add_u32 s14, s10, 0x12000
	s_addc_u32 s15, s11, 0
	global_load_dword v147, v4, s[14:15] offset:0
	global_load_dword v148, v4, s[14:15] offset:2048
	global_load_dword v149, v4, s[14:15] offset:64
	global_load_dword v150, v4, s[14:15] offset:2112
	global_load_dword v151, v4, s[14:15] offset:128
	global_load_dword v152, v4, s[14:15] offset:2176
	global_load_dword v153, v4, s[14:15] offset:192
	global_load_dword v154, v4, s[14:15] offset:2240
	s_add_u32 s14, s10, 0x13000
	s_addc_u32 s15, s11, 0
	global_load_dword v155, v4, s[14:15] offset:0
	global_load_dword v156, v4, s[14:15] offset:2048
	global_load_dword v157, v4, s[14:15] offset:64
	global_load_dword v158, v4, s[14:15] offset:2112
	global_load_dword v159, v4, s[14:15] offset:128
	global_load_dword v160, v4, s[14:15] offset:2176
	global_load_dword v161, v4, s[14:15] offset:192
	global_load_dword v162, v4, s[14:15] offset:2240
	s_waitcnt vmcnt(0)
; __device__ void scan_chain(PRef p, int l, int chain, ScanSm* sm) {
;     ...
;     {
;       const float* wu = p.a_w_up + ((size_t)(l * 2 + d) * 64) * 512 + hc;
;       const float* au = p.a_a_up + ((size_t)(l * 2 + d) * 64) * 512 + hc;
; #pragma unroll
;       for (int r = 0; r < 32; r++) {
;         pc.wu[r] = pack2(wu[(2 * r) * 512], wu[(2 * r + 1) * 512]);
;         pc.au[r] = pack2(au[(2 * r) * 512], au[(2 * r + 1) * 512]);
;       }
;     }
;     float* stw = &sm->st[wave][0][0];
;     const int base = (wave - 2) * 8;
;     int i = base, c = 0;
;     float Dprev = 1.f;
;     PrepRaw rwA, rwB, rnA, rnB;
;     prep_load(p, pc, b, d, i, rwA);
;     prep_load(p, pc, b, d, i + 1, rwB);
	v_cvt_pk_bf16_f32 v32, v98, v99
	v_cvt_pk_bf16_f32 v36, v100, v101
	v_cvt_pk_bf16_f32 v40, v102, v103
	v_cvt_pk_bf16_f32 v44, v104, v105
	v_cvt_pk_bf16_f32 v33, v106, v107
	v_cvt_pk_bf16_f32 v37, v108, v109
	v_cvt_pk_bf16_f32 v41, v110, v111
	v_cvt_pk_bf16_f32 v45, v112, v113
	v_cvt_pk_bf16_f32 v34, v114, v115
	v_cvt_pk_bf16_f32 v38, v116, v117
	v_cvt_pk_bf16_f32 v42, v118, v119
	v_cvt_pk_bf16_f32 v46, v120, v121
	v_cvt_pk_bf16_f32 v35, v122, v123
	v_cvt_pk_bf16_f32 v39, v124, v125
	v_cvt_pk_bf16_f32 v43, v126, v127
	v_cvt_pk_bf16_f32 v47, v128, v129
	v_cvt_pk_bf16_f32 v48, v130, v131
	v_cvt_pk_bf16_f32 v52, v133, v134
	v_cvt_pk_bf16_f32 v56, v135, v136
	v_cvt_pk_bf16_f32 v60, v137, v138
	v_cvt_pk_bf16_f32 v49, v139, v140
	v_cvt_pk_bf16_f32 v53, v141, v142
	v_cvt_pk_bf16_f32 v57, v143, v144
	v_cvt_pk_bf16_f32 v61, v145, v146
	v_cvt_pk_bf16_f32 v50, v147, v148
	v_cvt_pk_bf16_f32 v54, v149, v150
	v_cvt_pk_bf16_f32 v58, v151, v152
	v_cvt_pk_bf16_f32 v62, v153, v154
	v_cvt_pk_bf16_f32 v51, v155, v156
	v_cvt_pk_bf16_f32 v55, v157, v158
	v_cvt_pk_bf16_f32 v59, v159, v160
	v_cvt_pk_bf16_f32 v63, v161, v162
	s_add_u32 s14, s12, 0x0
	s_addc_u32 s15, s13, 0
	global_load_dword v98, v4, s[14:15] offset:0
	global_load_dword v99, v4, s[14:15] offset:2048
	global_load_dword v100, v4, s[14:15] offset:64
	global_load_dword v101, v4, s[14:15] offset:2112
	global_load_dword v102, v4, s[14:15] offset:128
	global_load_dword v103, v4, s[14:15] offset:2176
	global_load_dword v104, v4, s[14:15] offset:192
	global_load_dword v105, v4, s[14:15] offset:2240
	s_add_u32 s14, s12, 0x1000
	s_addc_u32 s15, s13, 0
	global_load_dword v106, v4, s[14:15] offset:0
	global_load_dword v107, v4, s[14:15] offset:2048
	global_load_dword v108, v4, s[14:15] offset:64
	global_load_dword v109, v4, s[14:15] offset:2112
	global_load_dword v110, v4, s[14:15] offset:128
	global_load_dword v111, v4, s[14:15] offset:2176
	global_load_dword v112, v4, s[14:15] offset:192
	global_load_dword v113, v4, s[14:15] offset:2240
	s_add_u32 s14, s12, 0x2000
	s_addc_u32 s15, s13, 0
	global_load_dword v114, v4, s[14:15] offset:0
	global_load_dword v115, v4, s[14:15] offset:2048
	global_load_dword v116, v4, s[14:15] offset:64
	global_load_dword v117, v4, s[14:15] offset:2112
	global_load_dword v118, v4, s[14:15] offset:128
	global_load_dword v119, v4, s[14:15] offset:2176
	global_load_dword v120, v4, s[14:15] offset:192
	global_load_dword v121, v4, s[14:15] offset:2240
	s_add_u32 s14, s12, 0x3000
	s_addc_u32 s15, s13, 0
	global_load_dword v122, v4, s[14:15] offset:0
	global_load_dword v123, v4, s[14:15] offset:2048
	global_load_dword v124, v4, s[14:15] offset:64
	global_load_dword v125, v4, s[14:15] offset:2112
	global_load_dword v126, v4, s[14:15] offset:128
	global_load_dword v127, v4, s[14:15] offset:2176
	global_load_dword v128, v4, s[14:15] offset:192
	global_load_dword v129, v4, s[14:15] offset:2240
	s_add_u32 s14, s12, 0x10000
	s_addc_u32 s15, s13, 0
	global_load_dword v130, v4, s[14:15] offset:0
	global_load_dword v131, v4, s[14:15] offset:2048
	global_load_dword v133, v4, s[14:15] offset:64
	global_load_dword v134, v4, s[14:15] offset:2112
	global_load_dword v135, v4, s[14:15] offset:128
	global_load_dword v136, v4, s[14:15] offset:2176
	global_load_dword v137, v4, s[14:15] offset:192
	global_load_dword v138, v4, s[14:15] offset:2240
	s_add_u32 s14, s12, 0x11000
	s_addc_u32 s15, s13, 0
	global_load_dword v139, v4, s[14:15] offset:0
	global_load_dword v140, v4, s[14:15] offset:2048
	global_load_dword v141, v4, s[14:15] offset:64
	global_load_dword v142, v4, s[14:15] offset:2112
	global_load_dword v143, v4, s[14:15] offset:128
	global_load_dword v144, v4, s[14:15] offset:2176
	global_load_dword v145, v4, s[14:15] offset:192
	global_load_dword v146, v4, s[14:15] offset:2240
	s_add_u32 s14, s12, 0x12000
	s_addc_u32 s15, s13, 0
	global_load_dword v147, v4, s[14:15] offset:0
	global_load_dword v148, v4, s[14:15] offset:2048
	global_load_dword v149, v4, s[14:15] offset:64
	global_load_dword v150, v4, s[14:15] offset:2112
	global_load_dword v151, v4, s[14:15] offset:128
	global_load_dword v152, v4, s[14:15] offset:2176
	global_load_dword v153, v4, s[14:15] offset:192
	global_load_dword v154, v4, s[14:15] offset:2240
	s_add_u32 s14, s12, 0x13000
	s_addc_u32 s15, s13, 0
	global_load_dword v155, v4, s[14:15] offset:0
	global_load_dword v156, v4, s[14:15] offset:2048
	global_load_dword v157, v4, s[14:15] offset:64
	global_load_dword v158, v4, s[14:15] offset:2112
	global_load_dword v159, v4, s[14:15] offset:128
	global_load_dword v160, v4, s[14:15] offset:2176
	global_load_dword v161, v4, s[14:15] offset:192
	global_load_dword v162, v4, s[14:15] offset:2240
	s_waitcnt vmcnt(0)
	v_cvt_pk_bf16_f32 v64, v98, v99
	v_cvt_pk_bf16_f32 v68, v100, v101
	v_cvt_pk_bf16_f32 v72, v102, v103
	v_cvt_pk_bf16_f32 v76, v104, v105
	v_cvt_pk_bf16_f32 v65, v106, v107
	v_cvt_pk_bf16_f32 v69, v108, v109
	v_cvt_pk_bf16_f32 v73, v110, v111
	v_cvt_pk_bf16_f32 v77, v112, v113
	v_cvt_pk_bf16_f32 v66, v114, v115
	v_cvt_pk_bf16_f32 v70, v116, v117
	v_cvt_pk_bf16_f32 v74, v118, v119
	v_cvt_pk_bf16_f32 v78, v120, v121
	v_cvt_pk_bf16_f32 v67, v122, v123
	v_cvt_pk_bf16_f32 v71, v124, v125
	v_cvt_pk_bf16_f32 v75, v126, v127
	v_cvt_pk_bf16_f32 v79, v128, v129
	v_cvt_pk_bf16_f32 v80, v130, v131
	v_cvt_pk_bf16_f32 v84, v133, v134
	v_cvt_pk_bf16_f32 v88, v135, v136
	v_cvt_pk_bf16_f32 v210, v137, v138
	v_cvt_pk_bf16_f32 v81, v139, v140
	v_cvt_pk_bf16_f32 v85, v141, v142
	v_cvt_pk_bf16_f32 v89, v143, v144
	v_cvt_pk_bf16_f32 v211, v145, v146
	v_cvt_pk_bf16_f32 v82, v147, v148
	v_cvt_pk_bf16_f32 v86, v149, v150
	v_cvt_pk_bf16_f32 v90, v151, v152
	v_cvt_pk_bf16_f32 v212, v153, v154
	v_cvt_pk_bf16_f32 v83, v155, v156
	v_cvt_pk_bf16_f32 v87, v157, v158
	v_cvt_pk_bf16_f32 v91, v159, v160
	v_cvt_pk_bf16_f32 v213, v161, v162
	s_cmp_eq_u32 s62, 0
	s_cselect_b64 s[4:5], -1, 0
	s_cmp_lg_u32 s62, 0
	s_cselect_b64 s[0:1], -1, 0
	v_readfirstlane_b32 s4, v12
	s_sub_u32 s4, s4, 2
	s_lshl_b32 s5, s4, 3
	s_cmp_eq_u32 s62, 0
	s_cbranch_scc1 .Lprep_fwd
	v_swap_b32 v14, v16
	v_swap_b32 v15, v17
	v_swap_b32 v18, v19
	v_swap_b32 v20, v21
	v_swap_b32 v22, v23
; DEV void prep_load(PRef p, const PrepConst& pc, int b, int d, int s, PrepRaw& rw) {
;   bool isctx = s < 256;
;   int pos = isctx ? (d ? 255 - s : s) : (d ? 2047 - (s - 256) : s - 256);
;   int seglen = isctx ? 256 : 2048;
;   int row = b * TPB + (isctx ? 0 : 256) + pos;
;   rw.row = row;
;   bool hp = pos > 0, hn = pos < seglen - 1;
;   const bf16* z = p.ZA + (size_t)row * 1792;
;   const bf16* zpp = hp ? z - 1792 : z;
;   const bf16* znp = hn ? z + 1792 : z;
;   rw.fp = hp ? 1.f : 0.f;
;   rw.fn = hn ? 1.f : 0.f;
; #pragma unroll
;   for (int i = 0; i < 5; i++) {
;     int col = pc.cols[i];
;     rw.zc[i] = z[col];
;     rw.zp[i] = zpp[col];
;     rw.zn[i] = znp[col];
;   }
; }
; __device__ void scan_chain(PRef p, int l, int chain, ScanSm* sm) {
;     ...
;     float* stw = &sm->st[wave][0][0];
;     const int base = (wave - 2) * 8;
;     int i = base, c = 0;
;     float Dprev = 1.f;
;     PrepRaw rwA, rwB, rnA, rnB;
;     prep_load(p, pc, b, d, i, rwA);
;     prep_load(p, pc, b, d, i + 1, rwB);
; #pragma unroll 1
;     while (c < 144) {
;       int i2 = i + 2, c2 = c;
;       if (i2 >= base + 8) { i2 = base; c2 = c + 1; }
;       if (c2 < 144) {
;         prep_load(p, pc, b, d, c2 * 16 + i2, rnA);
;         prep_load(p, pc, b, d, c2 * 16 + i2 + 1, rnB);
;       }
;       if (i == base) Dprev = 1.f;
;       prep_compute2(p, pc, rwA, rwB, h, d, &sm->rec[c & 1][i], &sm->rec[c & 1][i + 1], stw, lane, Dprev);
;       if (c2 != c) __syncthreads();
;       rwA = rnA;
;       rwB = rnB;
;       i = i2;
;       c = c2;
;     }
.Lprep_fwd:
	s_cmp_eq_u32 s62, 0
	s_mov_b32 s10, 0xfffff200
	s_cselect_b32 s10, 0xe00, s10
	s_cselect_b32 s11, 0, -1
	s_mov_b32 s9, 0xc1a00000
	s_lshl_b32 s0, s62, 5
	s_add_u32 s22, s18, s0
	s_addc_u32 s23, s19, 0
	s_lshl_b32 s0, s63, 2
	s_add_u32 s22, s22, s0
	s_addc_u32 s23, s23, 0
	v_lshlrev_b32_e32 v30, 1, v7
	v_lshlrev_b32_e32 v31, 1, v6
	v_add_u32_e32 v31, 0xc00, v31
	s_lshl_b32 s0, s4, 11
	v_and_b32_e32 v0, 7, v28
	v_lshrrev_b32_e32 v1, 4, v28
	v_lshlrev_b32_e32 v0, 8, v0
	v_lshl_add_u32 v0, v1, 4, v0
	v_add_u32_e32 v92, s0, v0
	v_lshl_add_u32 v97, v28, 1, s0
	s_lshl_b32 s1, s4, 12
	v_lshl_add_u32 v93, v28, 5, s1
	v_and_b32_e32 v0, 15, v28
	v_lshlrev_b32_e32 v0, 5, v0
	v_lshl_add_u32 v0, v1, 4, v0
	v_add_u32_e32 v95, s1, v0
	s_mul_i32 s0, s4, 0x3000
	v_lshl_add_u32 v94, v28, 2, s0
	v_sub_u32_e32 v0, 7, v28
	s_cmp_eq_u32 s62, 0
	s_cselect_b64 vcc, -1, 0
	s_nop 1
	v_cndmask_b32_e32 v0, v0, v28, vcc
	v_lshlrev_b32_e32 v174, 6, v0
	s_mov_b32 s0, s5
	s_cmp_lt_u32 s0, 0x100
	s_cselect_b32 s1, 0, 0x100
	s_movk_i32 s14, 0x7ff
	s_cselect_b32 s14, 0xff, s14
	s_sub_u32 s15, s0, s1
	s_sub_u32 s26, s14, s15
	s_cmp_eq_u32 s62, 0
	s_cselect_b32 s26, s15, s26
	s_add_u32 s1, s1, s28
	s_add_u32 s7, s1, s26
	s_cmp_lg_u32 s15, 0
	s_cselect_b32 s30, 1, 0
	s_add_u32 s15, s15, 7
	s_cmp_lg_u32 s15, s14
	s_cselect_b32 s31, 1, 0
	s_mul_i32 s1, s7, 0xe00
	s_add_u32 s16, s70, s1
	s_addc_u32 s17, s71, 0
	s_cmp_lg_u32 s30, 0
	s_cselect_b64 s[26:27], s[10:11], 0
	s_sub_u32 s26, s16, s26
	s_subb_u32 s27, s17, s27
	global_load_ushort v98, v30, s[26:27]
	global_load_ushort v99, v30, s[26:27] offset:1024
	global_load_ushort v100, v30, s[26:27] offset:2048
	global_load_ushort v101, v31, s[26:27]
	global_load_ushort v102, v31, s[26:27] offset:256
	global_load_ushort v103, v30, s[16:17]
	global_load_ushort v104, v30, s[16:17] offset:1024
	global_load_ushort v105, v30, s[16:17] offset:2048
	global_load_ushort v106, v31, s[16:17]
	global_load_ushort v107, v31, s[16:17] offset:256
	s_add_u32 s16, s16, s10
	s_addc_u32 s17, s17, s11
	global_load_ushort v108, v30, s[16:17]
	global_load_ushort v109, v30, s[16:17] offset:1024
	global_load_ushort v110, v30, s[16:17] offset:2048
	global_load_ushort v111, v31, s[16:17]
	global_load_ushort v112, v31, s[16:17] offset:256
	s_add_u32 s16, s16, s10
	s_addc_u32 s17, s17, s11
	global_load_ushort v113, v30, s[16:17]
	global_load_ushort v114, v30, s[16:17] offset:1024
	global_load_ushort v115, v30, s[16:17] offset:2048
	global_load_ushort v116, v31, s[16:17]
	global_load_ushort v117, v31, s[16:17] offset:256
	s_add_u32 s16, s16, s10
	s_addc_u32 s17, s17, s11
	global_load_ushort v118, v30, s[16:17]
	global_load_ushort v119, v30, s[16:17] offset:1024
	global_load_ushort v120, v30, s[16:17] offset:2048
	global_load_ushort v121, v31, s[16:17]
	global_load_ushort v122, v31, s[16:17] offset:256
	s_add_u32 s16, s16, s10
	s_addc_u32 s17, s17, s11
	global_load_ushort v123, v30, s[16:17]
	global_load_ushort v124, v30, s[16:17] offset:1024
	global_load_ushort v125, v30, s[16:17] offset:2048
	global_load_ushort v126, v31, s[16:17]
	global_load_ushort v127, v31, s[16:17] offset:256
	s_add_u32 s16, s16, s10
	s_addc_u32 s17, s17, s11
	global_load_ushort v128, v30, s[16:17]
	global_load_ushort v129, v30, s[16:17] offset:1024
	global_load_ushort v130, v30, s[16:17] offset:2048
	global_load_ushort v131, v31, s[16:17]
	global_load_ushort v133, v31, s[16:17] offset:256
	s_add_u32 s16, s16, s10
	s_addc_u32 s17, s17, s11
	global_load_ushort v134, v30, s[16:17]
	global_load_ushort v135, v30, s[16:17] offset:1024
	global_load_ushort v136, v30, s[16:17] offset:2048
	global_load_ushort v137, v31, s[16:17]
	global_load_ushort v138, v31, s[16:17] offset:256
	s_add_u32 s16, s16, s10
	s_addc_u32 s17, s17, s11
	global_load_ushort v139, v30, s[16:17]
	global_load_ushort v140, v30, s[16:17] offset:1024
	global_load_ushort v141, v30, s[16:17] offset:2048
	global_load_ushort v142, v31, s[16:17]
	global_load_ushort v143, v31, s[16:17] offset:256
	s_cmp_lg_u32 s31, 0
	s_cselect_b64 s[26:27], s[10:11], 0
	s_add_u32 s16, s16, s26
	s_addc_u32 s17, s17, s27
	global_load_ushort v144, v30, s[16:17]
	global_load_ushort v145, v30, s[16:17] offset:1024
	global_load_ushort v146, v30, s[16:17] offset:2048
	global_load_ushort v147, v31, s[16:17]
	global_load_ushort v148, v31, s[16:17] offset:256
	s_mov_b32 s8, 0
.Lprep_group:
	s_mov_b32 s6, s7
	s_mov_b32 s12, s30
	s_mov_b32 s13, s31
	s_and_b32 s0, s8, 1
	s_mulk_i32 s0, 0x6000
	v_add_u32_e32 v96, s0, v94
	s_waitcnt vmcnt(0)
	v_lshlrev_b32_e32 v98, 16, v98
	v_lshlrev_b32_e32 v99, 16, v99
	v_lshlrev_b32_e32 v100, 16, v100
	v_lshlrev_b32_e32 v101, 16, v101
	v_lshlrev_b32_e32 v102, 16, v102
	v_lshlrev_b32_e32 v103, 16, v103
	v_lshlrev_b32_e32 v104, 16, v104
	v_lshlrev_b32_e32 v105, 16, v105
	v_lshlrev_b32_e32 v106, 16, v106
	v_lshlrev_b32_e32 v107, 16, v107
	v_lshlrev_b32_e32 v108, 16, v108
	v_lshlrev_b32_e32 v109, 16, v109
	v_lshlrev_b32_e32 v110, 16, v110
	v_lshlrev_b32_e32 v111, 16, v111
	v_lshlrev_b32_e32 v112, 16, v112
	v_lshlrev_b32_e32 v113, 16, v113
	v_lshlrev_b32_e32 v114, 16, v114
	v_lshlrev_b32_e32 v115, 16, v115
	v_lshlrev_b32_e32 v116, 16, v116
	v_lshlrev_b32_e32 v117, 16, v117
	v_lshlrev_b32_e32 v118, 16, v118
	v_lshlrev_b32_e32 v119, 16, v119
	v_lshlrev_b32_e32 v120, 16, v120
	v_lshlrev_b32_e32 v121, 16, v121
	v_lshlrev_b32_e32 v122, 16, v122
	v_lshlrev_b32_e32 v123, 16, v123
	v_lshlrev_b32_e32 v124, 16, v124
	v_lshlrev_b32_e32 v125, 16, v125
	v_lshlrev_b32_e32 v126, 16, v126
	v_lshlrev_b32_e32 v127, 16, v127
	v_lshlrev_b32_e32 v128, 16, v128
	v_lshlrev_b32_e32 v129, 16, v129
	v_lshlrev_b32_e32 v130, 16, v130
	v_lshlrev_b32_e32 v131, 16, v131
	v_lshlrev_b32_e32 v133, 16, v133
	v_lshlrev_b32_e32 v134, 16, v134
	v_lshlrev_b32_e32 v135, 16, v135
	v_lshlrev_b32_e32 v136, 16, v136
	v_lshlrev_b32_e32 v137, 16, v137
	v_lshlrev_b32_e32 v138, 16, v138
	v_lshlrev_b32_e32 v139, 16, v139
	v_lshlrev_b32_e32 v140, 16, v140
	v_lshlrev_b32_e32 v141, 16, v141
	v_lshlrev_b32_e32 v142, 16, v142
	v_lshlrev_b32_e32 v143, 16, v143
	v_lshlrev_b32_e32 v144, 16, v144
	v_lshlrev_b32_e32 v145, 16, v145
	v_lshlrev_b32_e32 v146, 16, v146
	v_lshlrev_b32_e32 v147, 16, v147
	v_lshlrev_b32_e32 v148, 16, v148
	s_cmp_lg_u32 s12, 0
	s_cbranch_scc1 .Lprep_hasb
	v_mov_b32_e32 v98, 0
	v_mov_b32_e32 v99, 0
	v_mov_b32_e32 v100, 0
	v_mov_b32_e32 v101, 0
	v_mov_b32_e32 v102, 0
; DEV float bf2f(bf16 h) { return __uint_as_float(((uint32_t)h) << 16); }
; DEV void wbar() { __builtin_amdgcn_wave_barrier(); }
; DEV void prep_compute2(PRef p, const PrepConst& pc, const PrepRaw& rwA, const PrepRaw& rwB, int h, int d,
;                        ScanRec* rcA, ScanRec* rcB, float* stw, int lane, float& Dprev) {
;   float valsA[5], valsB[5];
; #pragma unroll
;   for (int i = 0; i < 5; i++) {
;     float zc = bf2f(rwA.zc[i]), zp = rwA.fp * bf2f(rwA.zp[i]), zn = rwA.fn * bf2f(rwA.zn[i]);
;     valsA[i] = zc + pc.mup[i] * (zp - zc) + pc.mun[i] * (zn - zc);
;     float zc2 = bf2f(rwB.zc[i]), zp2 = rwB.fp * bf2f(rwB.zp[i]), zn2 = rwB.fn * bf2f(rwB.zn[i]);
;     valsB[i] = zc2 + pc.mup[i] * (zp2 - zc2) + pc.mun[i] * (zn2 - zc2);
;   }
;   float thA = 1.f - __fdividef(2.f, 1.f + __expf(2.f * valsA[3]));
;   float thB = 1.f - __fdividef(2.f, 1.f + __expf(2.f * valsB[3]));
;   bf16* stb = (bf16*)stw;
;   wbar();
;   stb[lane] = f2bf(thA);
;   stb[64 + lane] = f2bf(valsA[4]);
;   stb[128 + lane] = f2bf(thB);
;   stb[192 + lane] = f2bf(valsB[4]);
;   wbar();
.Lprep_hasb:
	s_cmp_lg_u32 s13, 0
	s_cbranch_scc1 .Lprep_hasa
	v_mov_b32_e32 v144, 0
	v_mov_b32_e32 v145, 0
	v_mov_b32_e32 v146, 0
	v_mov_b32_e32 v147, 0
	v_mov_b32_e32 v148, 0
.Lprep_hasa:
	v_sub_f32_e32 v4, v106, v101
	v_sub_f32_e32 v5, v111, v106
	v_sub_f32_e32 v6, v116, v111
	v_sub_f32_e32 v7, v121, v116
	v_sub_f32_e32 v8, v126, v121
	v_sub_f32_e32 v9, v131, v126
	v_sub_f32_e32 v10, v137, v131
	v_sub_f32_e32 v11, v142, v137
	v_sub_f32_e32 v12, v147, v142
	v_fma_f32 v13, -v20, v4, v106
	v_fmac_f32_e32 v13, v21, v5
	v_fma_f32 v0, -v20, v5, v111
	v_fmac_f32_e32 v0, v21, v6
	v_fma_f32 v1, -v20, v6, v116
	v_fmac_f32_e32 v1, v21, v7
	v_fma_f32 v2, -v20, v7, v121
	v_fmac_f32_e32 v2, v21, v8
	v_fma_f32 v242, -v20, v8, v126
	v_fmac_f32_e32 v242, v21, v9
	v_fma_f32 v243, -v20, v9, v131
	v_fmac_f32_e32 v243, v21, v10
	v_fma_f32 v244, -v20, v10, v137
	v_fmac_f32_e32 v244, v21, v11
	v_fma_f32 v247, -v20, v11, v142
	v_fmac_f32_e32 v247, v21, v12
	v_sub_f32_e32 v4, v107, v102
	v_sub_f32_e32 v5, v112, v107
	v_sub_f32_e32 v6, v117, v112
	v_sub_f32_e32 v7, v122, v117
	v_sub_f32_e32 v8, v127, v122
	v_sub_f32_e32 v9, v133, v127
	v_sub_f32_e32 v10, v138, v133
	v_sub_f32_e32 v11, v143, v138
	v_sub_f32_e32 v12, v148, v143
	v_fma_f32 v248, -v22, v4, v107
	v_fmac_f32_e32 v248, v23, v5
	v_fma_f32 v249, -v22, v5, v112
	v_fmac_f32_e32 v249, v23, v6
	v_fma_f32 v250, -v22, v6, v117
	v_fmac_f32_e32 v250, v23, v7
	v_fma_f32 v251, -v22, v7, v122
	v_fmac_f32_e32 v251, v23, v8
	v_fma_f32 v252, -v22, v8, v127
	v_fmac_f32_e32 v252, v23, v9
	v_fma_f32 v253, -v22, v9, v133
	v_fmac_f32_e32 v253, v23, v10
	v_fma_f32 v254, -v22, v10, v138
	v_fmac_f32_e32 v254, v23, v11
	v_fma_f32 v255, -v22, v11, v143
	v_fmac_f32_e32 v255, v23, v12
	v_mul_f32_e32 v13, 0x4038aa3b, v13
	v_mul_f32_e32 v0, 0x4038aa3b, v0
	v_mul_f32_e32 v1, 0x4038aa3b, v1
	v_mul_f32_e32 v2, 0x4038aa3b, v2
	v_mul_f32_e32 v242, 0x4038aa3b, v242
	v_mul_f32_e32 v243, 0x4038aa3b, v243
	v_mul_f32_e32 v244, 0x4038aa3b, v244
	v_mul_f32_e32 v247, 0x4038aa3b, v247
	v_exp_f32_e32 v13, v13
	v_exp_f32_e32 v0, v0
	v_exp_f32_e32 v1, v1
	v_exp_f32_e32 v2, v2
	v_exp_f32_e32 v242, v242
	v_exp_f32_e32 v243, v243
	v_exp_f32_e32 v244, v244
	v_exp_f32_e32 v247, v247
	v_add_f32_e32 v13, 1.0, v13
	v_add_f32_e32 v0, 1.0, v0
	v_add_f32_e32 v1, 1.0, v1
	v_add_f32_e32 v2, 1.0, v2
	v_add_f32_e32 v242, 1.0, v242
	v_add_f32_e32 v243, 1.0, v243
	v_add_f32_e32 v244, 1.0, v244
	v_add_f32_e32 v247, 1.0, v247
	v_rcp_f32_e32 v13, v13
	v_rcp_f32_e32 v0, v0
	v_rcp_f32_e32 v1, v1
	v_rcp_f32_e32 v2, v2
	v_rcp_f32_e32 v242, v242
	v_rcp_f32_e32 v243, v243
	v_rcp_f32_e32 v244, v244
	v_rcp_f32_e32 v247, v247
	v_fma_f32 v13, v13, -2.0, 1.0
	v_fma_f32 v0, v0, -2.0, 1.0
	v_fma_f32 v1, v1, -2.0, 1.0
	v_fma_f32 v2, v2, -2.0, 1.0
	v_fma_f32 v242, v242, -2.0, 1.0
	v_fma_f32 v243, v243, -2.0, 1.0
	v_fma_f32 v244, v244, -2.0, 1.0
	v_fma_f32 v247, v247, -2.0, 1.0
	v_cvt_pk_bf16_f32 v13, v13, v248
	v_cvt_pk_bf16_f32 v0, v0, v249
	v_cvt_pk_bf16_f32 v1, v1, v250
	v_cvt_pk_bf16_f32 v2, v2, v251
	v_cvt_pk_bf16_f32 v242, v242, v252
	v_cvt_pk_bf16_f32 v243, v243, v253
	v_cvt_pk_bf16_f32 v244, v244, v254
	v_cvt_pk_bf16_f32 v247, v247, v255
	ds_write_b16 v97, v13 offset:49152
	ds_write_b16_d16_hi v97, v13 offset:49280
	ds_write_b16 v97, v0 offset:49408
	ds_write_b16_d16_hi v97, v0 offset:49536
	ds_write_b16 v97, v1 offset:49664
	ds_write_b16_d16_hi v97, v1 offset:49792
	ds_write_b16 v97, v2 offset:49920
	ds_write_b16_d16_hi v97, v2 offset:50048
	ds_write_b16 v97, v242 offset:50176
	ds_write_b16_d16_hi v97, v242 offset:50304
	ds_write_b16 v97, v243 offset:50432
	ds_write_b16_d16_hi v97, v243 offset:50560
	ds_write_b16 v97, v244 offset:50688
	ds_write_b16_d16_hi v97, v244 offset:50816
	ds_write_b16 v97, v247 offset:50944
	ds_write_b16_d16_hi v97, v247 offset:51072
	ds_read_b128 v[214:217], v92 offset:49152
	ds_read_b128 v[218:221], v92 offset:49216
	ds_read_b128 v[222:225], v92 offset:49280
	ds_read_b128 v[226:229], v92 offset:49344
	v_sub_f32_e32 v4, v103, v98
	v_sub_f32_e32 v5, v108, v103
	v_sub_f32_e32 v6, v113, v108
	v_sub_f32_e32 v7, v118, v113
	v_sub_f32_e32 v8, v123, v118
	v_sub_f32_e32 v9, v128, v123
	v_sub_f32_e32 v10, v134, v128
	v_sub_f32_e32 v11, v139, v134
	v_sub_f32_e32 v12, v144, v139
	v_fma_f32 v149, -v14, v4, v103
	v_fmac_f32_e32 v149, v16, v5
	v_fma_f32 v150, -v14, v5, v108
	v_fmac_f32_e32 v150, v16, v6
	v_fma_f32 v151, -v14, v6, v113
	v_fmac_f32_e32 v151, v16, v7
	v_fma_f32 v152, -v14, v7, v118
	v_fmac_f32_e32 v152, v16, v8
	v_fma_f32 v153, -v14, v8, v123
	v_fmac_f32_e32 v153, v16, v9
	v_fma_f32 v154, -v14, v9, v128
	v_fmac_f32_e32 v154, v16, v10
	v_fma_f32 v155, -v14, v10, v134
	v_fmac_f32_e32 v155, v16, v11
	v_fma_f32 v156, -v14, v11, v139
	v_fmac_f32_e32 v156, v16, v12
	v_sub_f32_e32 v4, v104, v99
	v_sub_f32_e32 v5, v109, v104
	v_sub_f32_e32 v6, v114, v109
	v_sub_f32_e32 v7, v119, v114
	v_sub_f32_e32 v8, v124, v119
	v_sub_f32_e32 v9, v129, v124
	v_sub_f32_e32 v10, v135, v129
	v_sub_f32_e32 v11, v140, v135
	v_sub_f32_e32 v12, v145, v140
	v_fma_f32 v157, -v15, v4, v104
	v_fmac_f32_e32 v157, v17, v5
	v_fma_f32 v158, -v15, v5, v109
	v_fmac_f32_e32 v158, v17, v6
	v_fma_f32 v159, -v15, v6, v114
	v_fmac_f32_e32 v159, v17, v7
	v_fma_f32 v160, -v15, v7, v119
	v_fmac_f32_e32 v160, v17, v8
	v_fma_f32 v161, -v15, v8, v124
	v_fmac_f32_e32 v161, v17, v9
	v_fma_f32 v162, -v15, v9, v129
	v_fmac_f32_e32 v162, v17, v10
	v_fma_f32 v163, -v15, v10, v135
	v_fmac_f32_e32 v163, v17, v11
	v_fma_f32 v164, -v15, v11, v140
	v_fmac_f32_e32 v164, v17, v12
	v_sub_f32_e32 v4, v105, v100
	v_sub_f32_e32 v5, v110, v105
	v_sub_f32_e32 v6, v115, v110
	v_sub_f32_e32 v7, v120, v115
	v_sub_f32_e32 v8, v125, v120
	v_sub_f32_e32 v9, v130, v125
	v_sub_f32_e32 v10, v136, v130
	v_sub_f32_e32 v11, v141, v136
	v_sub_f32_e32 v12, v146, v141
	v_fma_f32 v165, -v18, v4, v105
	v_fmac_f32_e32 v165, v19, v5
	v_fma_f32 v166, -v18, v5, v110
	v_fmac_f32_e32 v166, v19, v6
	v_fma_f32 v167, -v18, v6, v115
	v_fmac_f32_e32 v167, v19, v7
	v_fma_f32 v168, -v18, v7, v120
	v_fmac_f32_e32 v168, v19, v8
	v_fma_f32 v169, -v18, v8, v125
	v_fmac_f32_e32 v169, v19, v9
	v_fma_f32 v170, -v18, v9, v130
	v_fmac_f32_e32 v170, v19, v10
	v_fma_f32 v171, -v18, v10, v136
	v_fmac_f32_e32 v171, v19, v11
	v_fma_f32 v172, -v18, v11, v141
	v_fmac_f32_e32 v172, v19, v12
	s_waitcnt lgkmcnt(3)
; DEV void prep_compute2(PRef p, const PrepConst& pc, const PrepRaw& rwA, const PrepRaw& rwB, int h, int d,
;                        ScanRec* rcA, ScanRec* rcB, float* stw, int lane, float& Dprev) {
;     ...
;   float wA0 = pc.w0v, wA1 = 0.f, aA0 = pc.a0v, aA1 = 0.f;
;   float wB0 = pc.w0v, wB1 = 0.f, aB0 = pc.a0v, aB1 = 0.f;
;   const uint4* st4 = (const uint4*)stw;
; #pragma unroll
;   for (int g = 0; g < 8; g++) {
;     uint4 tA = st4[g], uA = st4[8 + g], tB = st4[16 + g], uB = st4[24 + g];
;     uint32_t w0 = pc.wu[4 * g], w1 = pc.wu[4 * g + 1], w2 = pc.wu[4 * g + 2], w3 = pc.wu[4 * g + 3];
;     uint32_t u0 = pc.au[4 * g], u1 = pc.au[4 * g + 1], u2 = pc.au[4 * g + 2], u3 = pc.au[4 * g + 3];
;     wA0 = dot2bf(tA.x, w0, wA0); wB0 = dot2bf(tB.x, w0, wB0);
;     wA1 = dot2bf(tA.y, w1, wA1); wB1 = dot2bf(tB.y, w1, wB1);
;     wA0 = dot2bf(tA.z, w2, wA0); wB0 = dot2bf(tB.z, w2, wB0);
;     wA1 = dot2bf(tA.w, w3, wA1); wB1 = dot2bf(tB.w, w3, wB1);
;     aA0 = dot2bf(uA.x, u0, aA0); aB0 = dot2bf(uB.x, u0, aB0);
;     aA1 = dot2bf(uA.y, u1, aA1); aB1 = dot2bf(uB.y, u1, aB1);
;     aA0 = dot2bf(uA.z, u2, aA0); aB0 = dot2bf(uB.z, u2, aB0);
;     aA1 = dot2bf(uA.w, u3, aA1); aB1 = dot2bf(uB.w, u3, aB1);
;   }
; __device__ void scan_chain(PRef p, int l, int chain, ScanSm* sm) {
;     ...
;     while (c < 144) {
;       int i2 = i + 2, c2 = c;
;       if (i2 >= base + 8) { i2 = base; c2 = c + 1; }
;       if (c2 < 144) {
;         prep_load(p, pc, b, d, c2 * 16 + i2, rnA);
;         prep_load(p, pc, b, d, c2 * 16 + i2 + 1, rnB);
;       }
	v_mfma_f32_16x16x32_bf16 v[230:233], v[214:217], v[32:35], 0
	v_mfma_f32_16x16x32_bf16 v[234:237], v[214:217], v[36:39], 0
	v_mfma_f32_16x16x32_bf16 v[238:241], v[214:217], v[40:43], 0
	v_mfma_f32_16x16x32_bf16 v[192:195], v[214:217], v[44:47], 0
	s_waitcnt lgkmcnt(2)
	v_mfma_f32_16x16x32_bf16 v[230:233], v[218:221], v[48:51], v[230:233]
	v_mfma_f32_16x16x32_bf16 v[234:237], v[218:221], v[52:55], v[234:237]
	v_mfma_f32_16x16x32_bf16 v[238:241], v[218:221], v[56:59], v[238:241]
	v_mfma_f32_16x16x32_bf16 v[192:195], v[218:221], v[60:63], v[192:195]
	s_waitcnt lgkmcnt(1)
	v_mfma_f32_16x16x32_bf16 v[4:7], v[222:225], v[64:67], 0
	v_mfma_f32_16x16x32_bf16 v[8:11], v[222:225], v[68:71], 0
	v_mfma_f32_16x16x32_bf16 v[248:251], v[222:225], v[72:75], 0
	v_mfma_f32_16x16x32_bf16 v[252:255], v[222:225], v[76:79], 0
	s_waitcnt lgkmcnt(0)
	v_mfma_f32_16x16x32_bf16 v[4:7], v[226:229], v[80:83], v[4:7]
	v_mfma_f32_16x16x32_bf16 v[8:11], v[226:229], v[84:87], v[8:11]
	v_mfma_f32_16x16x32_bf16 v[248:251], v[226:229], v[88:91], v[248:251]
	v_mfma_f32_16x16x32_bf16 v[252:255], v[226:229], v[210:213], v[252:255]
	s_cmp_lt_u32 s8, 0x8f
	s_cbranch_scc0 .Lprep_noissue
	s_add_u32 s0, s8, 1
	s_lshl_b32 s0, s0, 4
	s_add_u32 s0, s0, s5
	s_cmp_lt_u32 s0, 0x100
	s_cselect_b32 s1, 0, 0x100
	s_movk_i32 s14, 0x7ff
	s_cselect_b32 s14, 0xff, s14
	s_sub_u32 s15, s0, s1
	s_sub_u32 s26, s14, s15
	s_cmp_eq_u32 s62, 0
	s_cselect_b32 s26, s15, s26
	s_add_u32 s1, s1, s28
	s_add_u32 s7, s1, s26
	s_cmp_lg_u32 s15, 0
	s_cselect_b32 s30, 1, 0
	s_add_u32 s15, s15, 7
	s_cmp_lg_u32 s15, s14
	s_cselect_b32 s31, 1, 0
	s_mul_i32 s1, s7, 0xe00
	s_add_u32 s16, s70, s1
	s_addc_u32 s17, s71, 0
	s_cmp_lg_u32 s30, 0
	s_cselect_b64 s[26:27], s[10:11], 0
	s_sub_u32 s26, s16, s26
	s_subb_u32 s27, s17, s27
	global_load_ushort v98, v30, s[26:27]
	global_load_ushort v99, v30, s[26:27] offset:1024
	global_load_ushort v100, v30, s[26:27] offset:2048
	global_load_ushort v101, v31, s[26:27]
	global_load_ushort v102, v31, s[26:27] offset:256
	global_load_ushort v103, v30, s[16:17]
	global_load_ushort v104, v30, s[16:17] offset:1024
	global_load_ushort v105, v30, s[16:17] offset:2048
	global_load_ushort v106, v31, s[16:17]
	global_load_ushort v107, v31, s[16:17] offset:256
	s_add_u32 s16, s16, s10
	s_addc_u32 s17, s17, s11
	global_load_ushort v108, v30, s[16:17]
	global_load_ushort v109, v30, s[16:17] offset:1024
	global_load_ushort v110, v30, s[16:17] offset:2048
	global_load_ushort v111, v31, s[16:17]
	global_load_ushort v112, v31, s[16:17] offset:256
	s_add_u32 s16, s16, s10
	s_addc_u32 s17, s17, s11
	global_load_ushort v113, v30, s[16:17]
	global_load_ushort v114, v30, s[16:17] offset:1024
	global_load_ushort v115, v30, s[16:17] offset:2048
	global_load_ushort v116, v31, s[16:17]
	global_load_ushort v117, v31, s[16:17] offset:256
	s_add_u32 s16, s16, s10
	s_addc_u32 s17, s17, s11
	global_load_ushort v118, v30, s[16:17]
	global_load_ushort v119, v30, s[16:17] offset:1024
	global_load_ushort v120, v30, s[16:17] offset:2048
	global_load_ushort v121, v31, s[16:17]
	global_load_ushort v122, v31, s[16:17] offset:256
	s_add_u32 s16, s16, s10
	s_addc_u32 s17, s17, s11
	global_load_ushort v123, v30, s[16:17]
	global_load_ushort v124, v30, s[16:17] offset:1024
	global_load_ushort v125, v30, s[16:17] offset:2048
	global_load_ushort v126, v31, s[16:17]
	global_load_ushort v127, v31, s[16:17] offset:256
	s_add_u32 s16, s16, s10
	s_addc_u32 s17, s17, s11
	global_load_ushort v128, v30, s[16:17]
	global_load_ushort v129, v30, s[16:17] offset:1024
	global_load_ushort v130, v30, s[16:17] offset:2048
	global_load_ushort v131, v31, s[16:17]
	global_load_ushort v133, v31, s[16:17] offset:256
	s_add_u32 s16, s16, s10
	s_addc_u32 s17, s17, s11
	global_load_ushort v134, v30, s[16:17]
	global_load_ushort v135, v30, s[16:17] offset:1024
	global_load_ushort v136, v30, s[16:17] offset:2048
	global_load_ushort v137, v31, s[16:17]
	global_load_ushort v138, v31, s[16:17] offset:256
	s_add_u32 s16, s16, s10
	s_addc_u32 s17, s17, s11
	global_load_ushort v139, v30, s[16:17]
	global_load_ushort v140, v30, s[16:17] offset:1024
	global_load_ushort v141, v30, s[16:17] offset:2048
	global_load_ushort v142, v31, s[16:17]
	global_load_ushort v143, v31, s[16:17] offset:256
	s_cmp_lg_u32 s31, 0
	s_cselect_b64 s[26:27], s[10:11], 0
	s_add_u32 s16, s16, s26
	s_addc_u32 s17, s17, s27
	global_load_ushort v144, v30, s[16:17]
	global_load_ushort v145, v30, s[16:17] offset:1024
	global_load_ushort v146, v30, s[16:17] offset:2048
	global_load_ushort v147, v31, s[16:17]
	global_load_ushort v148, v31, s[16:17] offset:256
; DEV void prep_compute2(PRef p, const PrepConst& pc, const PrepRaw& rwA, const PrepRaw& rwB, int h, int d,
;                        ScanRec* rcA, ScanRec* rcB, float* stw, int lane, float& Dprev) {
;     ...
;   float zzA = -(wA0 + wA1), zzB = -(wB0 + wB1);
;   float spA = zzA > 20.f ? zzA : __logf(1.f + __expf(zzA));
;   float spB = zzB > 20.f ? zzB : __logf(1.f + __expf(zzB));
;   float decA = __expf(-__expf(-spA - 0.5f)), decB = __expf(-__expf(-spB - 0.5f));
;   float aA = __fdividef(1.f, 1.f + __expf(-(aA0 + aA1))), aB = __fdividef(1.f, 1.f + __expf(-(aB0 + aB1)));
;   float kkA = valsA[1] * pc.kkc, kkB = valsB[1] * pc.kkc;
;   float ssA = wave_sum(kkA * kkA), ssB = wave_sum(kkB * kkB);
;   kkA *= rsqrtf(fmaxf(ssA, 1e-24f));
;   kkB *= rsqrtf(fmaxf(ssB, 1e-24f));
;   float kdA = valsA[1] * (1.f + (aA - 1.f) * pc.kac), kdB = valsB[1] * (1.f + (aB - 1.f) * pc.kac);
;   float bonA = wave_sum(valsA[0] * kdA * pc.rkc), bonB = wave_sum(valsB[0] * kdB * pc.rkc);
.Lprep_noissue:
	s_nop 7
	s_mov_b32 exec_hi, 0
	ds_write_b128 v95, v[230:233] offset:55328
	ds_write_b128 v95, v[234:237] offset:55840
	ds_write_b128 v95, v[238:241] offset:56352
	ds_write_b128 v95, v[192:195] offset:56864
	ds_write_b128 v95, v[4:7] offset:57376
	ds_write_b128 v95, v[8:11] offset:57888
	ds_write_b128 v95, v[248:251] offset:58400
	ds_write_b128 v95, v[252:255] offset:58912
	s_mov_b32 exec_hi, -1
	ds_read_b128 v[176:179], v93 offset:55328
	ds_read_b128 v[180:183], v93 offset:55344
	ds_read_b128 v[184:187], v93 offset:57376
	ds_read_b128 v[188:191], v93 offset:57392
	s_waitcnt lgkmcnt(0)
	v_add_f32_e32 v176, v24, v176
	v_add_f32_e32 v177, v24, v177
	v_add_f32_e32 v178, v24, v178
	v_add_f32_e32 v179, v24, v179
	v_add_f32_e32 v180, v24, v180
	v_add_f32_e32 v181, v24, v181
	v_add_f32_e32 v182, v24, v182
	v_add_f32_e32 v183, v24, v183
	v_add_f32_e32 v184, v25, v184
	v_add_f32_e32 v185, v25, v185
	v_add_f32_e32 v186, v25, v186
	v_add_f32_e32 v187, v25, v187
	v_add_f32_e32 v188, v25, v188
	v_add_f32_e32 v189, v25, v189
	v_add_f32_e32 v190, v25, v190
	v_add_f32_e32 v191, v25, v191
	v_mul_f32_e32 v4, 0xbfb8aa3b, v176
	v_mul_f32_e32 v5, 0xbfb8aa3b, v177
	v_mul_f32_e32 v6, 0xbfb8aa3b, v178
	v_mul_f32_e32 v7, 0xbfb8aa3b, v179
	v_mul_f32_e32 v8, 0xbfb8aa3b, v184
	v_mul_f32_e32 v9, 0xbfb8aa3b, v185
	v_mul_f32_e32 v10, 0xbfb8aa3b, v186
	v_mul_f32_e32 v11, 0xbfb8aa3b, v187
	v_exp_f32_e32 v4, v4
	v_exp_f32_e32 v5, v5
	v_exp_f32_e32 v6, v6
	v_exp_f32_e32 v7, v7
	v_exp_f32_e32 v8, v8
	v_exp_f32_e32 v9, v9
	v_exp_f32_e32 v10, v10
	v_exp_f32_e32 v11, v11
	v_add_f32_e32 v4, 1.0, v4
	v_add_f32_e32 v5, 1.0, v5
	v_add_f32_e32 v6, 1.0, v6
	v_add_f32_e32 v7, 1.0, v7
	v_add_f32_e32 v8, 1.0, v8
	v_add_f32_e32 v9, 1.0, v9
	v_add_f32_e32 v10, 1.0, v10
	v_add_f32_e32 v11, 1.0, v11
	v_log_f32_e32 v4, v4
	v_log_f32_e32 v5, v5
	v_log_f32_e32 v6, v6
	v_log_f32_e32 v7, v7
	v_rcp_f32_e32 v184, v8
	v_rcp_f32_e32 v185, v9
	v_rcp_f32_e32 v186, v10
	v_rcp_f32_e32 v187, v11
	v_mul_f32_e32 v4, 0x3f317218, v4
	v_mul_f32_e32 v5, 0x3f317218, v5
	v_mul_f32_e32 v6, 0x3f317218, v6
	v_mul_f32_e32 v7, 0x3f317218, v7
	v_cmp_gt_f32_e32 vcc, s9, v176
	s_nop 1
	v_cndmask_b32_e64 v4, v4, -v176, vcc
	v_cmp_gt_f32_e32 vcc, s9, v177
	s_nop 1
	v_cndmask_b32_e64 v5, v5, -v177, vcc
	v_cmp_gt_f32_e32 vcc, s9, v178
	s_nop 1
	v_cndmask_b32_e64 v6, v6, -v178, vcc
	v_cmp_gt_f32_e32 vcc, s9, v179
	s_nop 1
	v_cndmask_b32_e64 v7, v7, -v179, vcc
	v_sub_f32_e32 v4, -0.5, v4
	v_sub_f32_e32 v5, -0.5, v5
	v_sub_f32_e32 v6, -0.5, v6
	v_sub_f32_e32 v7, -0.5, v7
	v_mul_f32_e32 v4, 0x3fb8aa3b, v4
	v_mul_f32_e32 v5, 0x3fb8aa3b, v5
	v_mul_f32_e32 v6, 0x3fb8aa3b, v6
	v_mul_f32_e32 v7, 0x3fb8aa3b, v7
	v_exp_f32_e32 v4, v4
	v_exp_f32_e32 v5, v5
	v_exp_f32_e32 v6, v6
	v_exp_f32_e32 v7, v7
	v_mul_f32_e32 v4, 0xbfb8aa3b, v4
	v_mul_f32_e32 v5, 0xbfb8aa3b, v5
	v_mul_f32_e32 v6, 0xbfb8aa3b, v6
	v_mul_f32_e32 v7, 0xbfb8aa3b, v7
	v_exp_f32_e32 v176, v4
	v_exp_f32_e32 v177, v5
	v_exp_f32_e32 v178, v6
	v_exp_f32_e32 v179, v7
	v_mul_f32_e32 v4, 0xbfb8aa3b, v180
	v_mul_f32_e32 v5, 0xbfb8aa3b, v181
	v_mul_f32_e32 v6, 0xbfb8aa3b, v182
	v_mul_f32_e32 v7, 0xbfb8aa3b, v183
	v_mul_f32_e32 v8, 0xbfb8aa3b, v188
	v_mul_f32_e32 v9, 0xbfb8aa3b, v189
	v_mul_f32_e32 v10, 0xbfb8aa3b, v190
	v_mul_f32_e32 v11, 0xbfb8aa3b, v191
	v_exp_f32_e32 v4, v4
	v_exp_f32_e32 v5, v5
	v_exp_f32_e32 v6, v6
	v_exp_f32_e32 v7, v7
	v_exp_f32_e32 v8, v8
	v_exp_f32_e32 v9, v9
	v_exp_f32_e32 v10, v10
	v_exp_f32_e32 v11, v11
	v_add_f32_e32 v4, 1.0, v4
	v_add_f32_e32 v5, 1.0, v5
	v_add_f32_e32 v6, 1.0, v6
	v_add_f32_e32 v7, 1.0, v7
	v_add_f32_e32 v8, 1.0, v8
	v_add_f32_e32 v9, 1.0, v9
	v_add_f32_e32 v10, 1.0, v10
	v_add_f32_e32 v11, 1.0, v11
	v_log_f32_e32 v4, v4
	v_log_f32_e32 v5, v5
	v_log_f32_e32 v6, v6
	v_log_f32_e32 v7, v7
	v_rcp_f32_e32 v188, v8
	v_rcp_f32_e32 v189, v9
	v_rcp_f32_e32 v190, v10
	v_rcp_f32_e32 v191, v11
	v_mul_f32_e32 v4, 0x3f317218, v4
	v_mul_f32_e32 v5, 0x3f317218, v5
	v_mul_f32_e32 v6, 0x3f317218, v6
	v_mul_f32_e32 v7, 0x3f317218, v7
	v_cmp_gt_f32_e32 vcc, s9, v180
	s_nop 1
	v_cndmask_b32_e64 v4, v4, -v180, vcc
	v_cmp_gt_f32_e32 vcc, s9, v181
	s_nop 1
	v_cndmask_b32_e64 v5, v5, -v181, vcc
	v_cmp_gt_f32_e32 vcc, s9, v182
	s_nop 1
	v_cndmask_b32_e64 v6, v6, -v182, vcc
	v_cmp_gt_f32_e32 vcc, s9, v183
	s_nop 1
	v_cndmask_b32_e64 v7, v7, -v183, vcc
	v_sub_f32_e32 v4, -0.5, v4
	v_sub_f32_e32 v5, -0.5, v5
	v_sub_f32_e32 v6, -0.5, v6
	v_sub_f32_e32 v7, -0.5, v7
	v_mul_f32_e32 v4, 0x3fb8aa3b, v4
	v_mul_f32_e32 v5, 0x3fb8aa3b, v5
	v_mul_f32_e32 v6, 0x3fb8aa3b, v6
	v_mul_f32_e32 v7, 0x3fb8aa3b, v7
	v_exp_f32_e32 v4, v4
	v_exp_f32_e32 v5, v5
	v_exp_f32_e32 v6, v6
	v_exp_f32_e32 v7, v7
	v_mul_f32_e32 v4, 0xbfb8aa3b, v4
	v_mul_f32_e32 v5, 0xbfb8aa3b, v5
	v_mul_f32_e32 v6, 0xbfb8aa3b, v6
	v_mul_f32_e32 v7, 0xbfb8aa3b, v7
	v_exp_f32_e32 v180, v4
	v_exp_f32_e32 v181, v5
	v_exp_f32_e32 v182, v6
	v_exp_f32_e32 v183, v7
	v_mov_b32_e32 v249, 1.0
	v_mul_f32_e32 v4, v26, v157
	v_mul_f32_e32 v5, v26, v158
	v_add_f32_e32 v6, -1.0, v184
	v_add_f32_e32 v7, -1.0, v185
	v_mul_f32_e32 v8, v4, v4
	v_mul_f32_e32 v9, v5, v5
	v_fma_f32 v6, v27, v6, 1.0
	v_fma_f32 v7, v27, v7, 1.0
	v_mul_f32_e32 v6, v157, v6
	v_mul_f32_e32 v7, v158, v7
	v_mul_f32_e32 v10, v149, v6
	v_mul_f32_e32 v11, v150, v7
	v_mul_f32_e32 v10, v29, v10
	v_mul_f32_e32 v11, v29, v11
	v_add_f32_dpp v8, v8, v8 quad_perm:[1,0,3,2] row_mask:0xf bank_mask:0xf
	v_add_f32_dpp v9, v9, v9 quad_perm:[1,0,3,2] row_mask:0xf bank_mask:0xf
	v_add_f32_dpp v10, v10, v10 quad_perm:[1,0,3,2] row_mask:0xf bank_mask:0xf
	v_add_f32_dpp v11, v11, v11 quad_perm:[1,0,3,2] row_mask:0xf bank_mask:0xf
; DEV void prep_compute2(PRef p, const PrepConst& pc, const PrepRaw& rwA, const PrepRaw& rwB, int h, int d,
;                        ScanRec* rcA, ScanRec* rcB, float* stw, int lane, float& Dprev) {
;     ...
;   float kkA = valsA[1] * pc.kkc, kkB = valsB[1] * pc.kkc;
;   float ssA = wave_sum(kkA * kkA), ssB = wave_sum(kkB * kkB);
;   kkA *= rsqrtf(fmaxf(ssA, 1e-24f));
;   kkB *= rsqrtf(fmaxf(ssB, 1e-24f));
;   float kdA = valsA[1] * (1.f + (aA - 1.f) * pc.kac), kdB = valsB[1] * (1.f + (aB - 1.f) * pc.kac);
;   float bonA = wave_sum(valsA[0] * kdA * pc.rkc), bonB = wave_sum(valsB[0] * kdB * pc.rkc);
;   float DA = Dprev * decA, DB = DA * decB;
;   float iDA = __fdividef(1.f, DA), iDB = __fdividef(1.f, DB);
;   rcA->w[lane] = DA; rcB->w[lane] = DB;
;   rcA->kk[lane] = kkA * Dprev; rcB->kk[lane] = kkB * DA;
;   rcA->kka[lane] = kkA * aA * iDA; rcB->kka[lane] = kkB * aB * iDB;
;   rcA->kd[lane] = kdA * iDA; rcB->kd[lane] = kdB * iDB;
;   rcA->r[lane] = valsA[0] * DA; rcB->r[lane] = valsB[0] * DB;
;   rcA->v[lane] = valsA[2]; rcB->v[lane] = valsB[2];
;   Dprev = DB;
;   if (lane == 0) {
;     p.SB[(size_t)rwA.row * 16 + d * 8 + h] = bonA;
;     p.SB[(size_t)rwB.row * 16 + d * 8 + h] = bonB;
	v_add_f32_dpp v8, v8, v8 quad_perm:[2,3,0,1] row_mask:0xf bank_mask:0xf
	v_add_f32_dpp v9, v9, v9 quad_perm:[2,3,0,1] row_mask:0xf bank_mask:0xf
	v_add_f32_dpp v10, v10, v10 quad_perm:[2,3,0,1] row_mask:0xf bank_mask:0xf
	v_add_f32_dpp v11, v11, v11 quad_perm:[2,3,0,1] row_mask:0xf bank_mask:0xf
	v_add_f32_dpp v8, v8, v8 row_half_mirror row_mask:0xf bank_mask:0xf
	v_add_f32_dpp v9, v9, v9 row_half_mirror row_mask:0xf bank_mask:0xf
	v_add_f32_dpp v10, v10, v10 row_half_mirror row_mask:0xf bank_mask:0xf
	v_add_f32_dpp v11, v11, v11 row_half_mirror row_mask:0xf bank_mask:0xf
	v_add_f32_dpp v8, v8, v8 row_mirror row_mask:0xf bank_mask:0xf
	v_add_f32_dpp v9, v9, v9 row_mirror row_mask:0xf bank_mask:0xf
	v_add_f32_dpp v10, v10, v10 row_mirror row_mask:0xf bank_mask:0xf
	v_add_f32_dpp v11, v11, v11 row_mirror row_mask:0xf bank_mask:0xf
	v_add_f32_dpp v8, v8, v8 row_bcast:15 row_mask:0xa bank_mask:0xf
	v_add_f32_dpp v9, v9, v9 row_bcast:15 row_mask:0xa bank_mask:0xf
	v_add_f32_dpp v10, v10, v10 row_bcast:15 row_mask:0xa bank_mask:0xf
	v_add_f32_dpp v11, v11, v11 row_bcast:15 row_mask:0xa bank_mask:0xf
	v_add_f32_dpp v8, v8, v8 row_bcast:31 row_mask:0xc bank_mask:0xf
	v_add_f32_dpp v9, v9, v9 row_bcast:31 row_mask:0xc bank_mask:0xf
	v_add_f32_dpp v10, v10, v10 row_bcast:31 row_mask:0xc bank_mask:0xf
	v_add_f32_dpp v11, v11, v11 row_bcast:31 row_mask:0xc bank_mask:0xf
	v_readlane_b32 s0, v8, 63
	v_readlane_b32 s1, v9, 63
	v_readlane_b32 s14, v10, 63
	v_readlane_b32 s15, v11, 63
	v_mov_b32_e32 v8, s0
	v_mov_b32_e32 v9, s1
	v_max_f32_e32 v8, 0x179abe15, v8
	v_max_f32_e32 v9, 0x179abe15, v9
	v_rsq_f32_e32 v8, v8
	v_rsq_f32_e32 v9, v9
	v_mul_f32_e32 v12, v249, v176
	v_mul_f32_e32 v250, v12, v177
	v_mul_f32_e32 v4, v4, v8
	v_mul_f32_e32 v5, v5, v9
	v_rcp_f32_e32 v8, v12
	v_rcp_f32_e32 v9, v250
	v_writelane_b32 v173, s14, 0
	v_writelane_b32 v173, s15, 1
	v_mul_f32_e32 v0, v184, v4
	v_mul_f32_e32 v1, v185, v5
	v_mul_f32_e32 v2, v249, v4
	v_mul_f32_e32 v0, v8, v0
	v_mul_f32_e32 v242, v8, v6
	v_mul_f32_e32 v1, v9, v1
	v_mul_f32_e32 v243, v9, v7
	v_mul_f32_e32 v244, v12, v5
	v_mul_f32_e32 v247, v149, v12
	v_mul_f32_e32 v248, v150, v250
	ds_write2st64_b32 v96, v12, v2 offset0:0 offset1:1
	ds_write2st64_b32 v96, v0, v242 offset0:2 offset1:3
	ds_write2st64_b32 v96, v247, v165 offset0:4 offset1:5
	ds_write2st64_b32 v96, v250, v244 offset0:6 offset1:7
	ds_write2st64_b32 v96, v1, v243 offset0:8 offset1:9
	ds_write2st64_b32 v96, v248, v166 offset0:10 offset1:11
	v_mul_f32_e32 v4, v26, v159
	v_mul_f32_e32 v5, v26, v160
	v_add_f32_e32 v6, -1.0, v186
	v_add_f32_e32 v7, -1.0, v187
	v_mul_f32_e32 v8, v4, v4
	v_mul_f32_e32 v9, v5, v5
	v_fma_f32 v6, v27, v6, 1.0
	v_fma_f32 v7, v27, v7, 1.0
	v_mul_f32_e32 v6, v159, v6
	v_mul_f32_e32 v7, v160, v7
	v_mul_f32_e32 v10, v151, v6
	v_mul_f32_e32 v11, v152, v7
	v_mul_f32_e32 v10, v29, v10
	v_mul_f32_e32 v11, v29, v11
	v_add_f32_dpp v8, v8, v8 quad_perm:[1,0,3,2] row_mask:0xf bank_mask:0xf
	v_add_f32_dpp v9, v9, v9 quad_perm:[1,0,3,2] row_mask:0xf bank_mask:0xf
	v_add_f32_dpp v10, v10, v10 quad_perm:[1,0,3,2] row_mask:0xf bank_mask:0xf
	v_add_f32_dpp v11, v11, v11 quad_perm:[1,0,3,2] row_mask:0xf bank_mask:0xf
	v_add_f32_dpp v8, v8, v8 quad_perm:[2,3,0,1] row_mask:0xf bank_mask:0xf
	v_add_f32_dpp v9, v9, v9 quad_perm:[2,3,0,1] row_mask:0xf bank_mask:0xf
	v_add_f32_dpp v10, v10, v10 quad_perm:[2,3,0,1] row_mask:0xf bank_mask:0xf
	v_add_f32_dpp v11, v11, v11 quad_perm:[2,3,0,1] row_mask:0xf bank_mask:0xf
	v_add_f32_dpp v8, v8, v8 row_half_mirror row_mask:0xf bank_mask:0xf
	v_add_f32_dpp v9, v9, v9 row_half_mirror row_mask:0xf bank_mask:0xf
	v_add_f32_dpp v10, v10, v10 row_half_mirror row_mask:0xf bank_mask:0xf
	v_add_f32_dpp v11, v11, v11 row_half_mirror row_mask:0xf bank_mask:0xf
	v_add_f32_dpp v8, v8, v8 row_mirror row_mask:0xf bank_mask:0xf
	v_add_f32_dpp v9, v9, v9 row_mirror row_mask:0xf bank_mask:0xf
	v_add_f32_dpp v10, v10, v10 row_mirror row_mask:0xf bank_mask:0xf
	v_add_f32_dpp v11, v11, v11 row_mirror row_mask:0xf bank_mask:0xf
	v_add_f32_dpp v8, v8, v8 row_bcast:15 row_mask:0xa bank_mask:0xf
	v_add_f32_dpp v9, v9, v9 row_bcast:15 row_mask:0xa bank_mask:0xf
	v_add_f32_dpp v10, v10, v10 row_bcast:15 row_mask:0xa bank_mask:0xf
	v_add_f32_dpp v11, v11, v11 row_bcast:15 row_mask:0xa bank_mask:0xf
	v_add_f32_dpp v8, v8, v8 row_bcast:31 row_mask:0xc bank_mask:0xf
	v_add_f32_dpp v9, v9, v9 row_bcast:31 row_mask:0xc bank_mask:0xf
	v_add_f32_dpp v10, v10, v10 row_bcast:31 row_mask:0xc bank_mask:0xf
	v_add_f32_dpp v11, v11, v11 row_bcast:31 row_mask:0xc bank_mask:0xf
	v_readlane_b32 s0, v8, 63
	v_readlane_b32 s1, v9, 63
	v_readlane_b32 s14, v10, 63
	v_readlane_b32 s15, v11, 63
	v_mov_b32_e32 v8, s0
	v_mov_b32_e32 v9, s1
	v_max_f32_e32 v8, 0x179abe15, v8
	v_max_f32_e32 v9, 0x179abe15, v9
	v_rsq_f32_e32 v8, v8
	v_rsq_f32_e32 v9, v9
	v_mul_f32_e32 v12, v250, v178
	v_mul_f32_e32 v249, v12, v179
	v_mul_f32_e32 v4, v4, v8
	v_mul_f32_e32 v5, v5, v9
	v_rcp_f32_e32 v8, v12
	v_rcp_f32_e32 v9, v249
	v_writelane_b32 v173, s14, 2
	v_writelane_b32 v173, s15, 3
	v_mul_f32_e32 v0, v186, v4
	v_mul_f32_e32 v1, v187, v5
	v_mul_f32_e32 v2, v250, v4
	v_mul_f32_e32 v0, v8, v0
	v_mul_f32_e32 v242, v8, v6
	v_mul_f32_e32 v1, v9, v1
	v_mul_f32_e32 v243, v9, v7
	v_mul_f32_e32 v244, v12, v5
	v_mul_f32_e32 v247, v151, v12
	v_mul_f32_e32 v248, v152, v249
	ds_write2st64_b32 v96, v12, v2 offset0:12 offset1:13
	ds_write2st64_b32 v96, v0, v242 offset0:14 offset1:15
	ds_write2st64_b32 v96, v247, v167 offset0:16 offset1:17
	ds_write2st64_b32 v96, v249, v244 offset0:18 offset1:19
	ds_write2st64_b32 v96, v1, v243 offset0:20 offset1:21
	ds_write2st64_b32 v96, v248, v168 offset0:22 offset1:23
; DEV void prep_compute2(PRef p, const PrepConst& pc, const PrepRaw& rwA, const PrepRaw& rwB, int h, int d,
;                        ScanRec* rcA, ScanRec* rcB, float* stw, int lane, float& Dprev) {
;     ...
;   float kkA = valsA[1] * pc.kkc, kkB = valsB[1] * pc.kkc;
;   float ssA = wave_sum(kkA * kkA), ssB = wave_sum(kkB * kkB);
;   kkA *= rsqrtf(fmaxf(ssA, 1e-24f));
;   kkB *= rsqrtf(fmaxf(ssB, 1e-24f));
;   float kdA = valsA[1] * (1.f + (aA - 1.f) * pc.kac), kdB = valsB[1] * (1.f + (aB - 1.f) * pc.kac);
;   float bonA = wave_sum(valsA[0] * kdA * pc.rkc), bonB = wave_sum(valsB[0] * kdB * pc.rkc);
;   float DA = Dprev * decA, DB = DA * decB;
;   float iDA = __fdividef(1.f, DA), iDB = __fdividef(1.f, DB);
;   rcA->w[lane] = DA; rcB->w[lane] = DB;
;   rcA->kk[lane] = kkA * Dprev; rcB->kk[lane] = kkB * DA;
;   rcA->kka[lane] = kkA * aA * iDA; rcB->kka[lane] = kkB * aB * iDB;
;   rcA->kd[lane] = kdA * iDA; rcB->kd[lane] = kdB * iDB;
;   rcA->r[lane] = valsA[0] * DA; rcB->r[lane] = valsB[0] * DB;
;   rcA->v[lane] = valsA[2]; rcB->v[lane] = valsB[2];
;   Dprev = DB;
;   if (lane == 0) {
;     p.SB[(size_t)rwA.row * 16 + d * 8 + h] = bonA;
;     p.SB[(size_t)rwB.row * 16 + d * 8 + h] = bonB;
;   }
; __device__ void scan_chain(PRef p, int l, int chain, ScanSm* sm) {
;     ...
;       if (i == base) Dprev = 1.f;
;       prep_compute2(p, pc, rwA, rwB, h, d, &sm->rec[c & 1][i], &sm->rec[c & 1][i + 1], stw, lane, Dprev);
;       if (c2 != c) __syncthreads();
;       rwA = rnA;
;       rwB = rnB;
;       i = i2;
;       c = c2;
;     }
	v_mul_f32_e32 v4, v26, v161
	v_mul_f32_e32 v5, v26, v162
	v_add_f32_e32 v6, -1.0, v188
	v_add_f32_e32 v7, -1.0, v189
	v_mul_f32_e32 v8, v4, v4
	v_mul_f32_e32 v9, v5, v5
	v_fma_f32 v6, v27, v6, 1.0
	v_fma_f32 v7, v27, v7, 1.0
	v_mul_f32_e32 v6, v161, v6
	v_mul_f32_e32 v7, v162, v7
	v_mul_f32_e32 v10, v153, v6
	v_mul_f32_e32 v11, v154, v7
	v_mul_f32_e32 v10, v29, v10
	v_mul_f32_e32 v11, v29, v11
	v_add_f32_dpp v8, v8, v8 quad_perm:[1,0,3,2] row_mask:0xf bank_mask:0xf
	v_add_f32_dpp v9, v9, v9 quad_perm:[1,0,3,2] row_mask:0xf bank_mask:0xf
	v_add_f32_dpp v10, v10, v10 quad_perm:[1,0,3,2] row_mask:0xf bank_mask:0xf
	v_add_f32_dpp v11, v11, v11 quad_perm:[1,0,3,2] row_mask:0xf bank_mask:0xf
	v_add_f32_dpp v8, v8, v8 quad_perm:[2,3,0,1] row_mask:0xf bank_mask:0xf
	v_add_f32_dpp v9, v9, v9 quad_perm:[2,3,0,1] row_mask:0xf bank_mask:0xf
	v_add_f32_dpp v10, v10, v10 quad_perm:[2,3,0,1] row_mask:0xf bank_mask:0xf
	v_add_f32_dpp v11, v11, v11 quad_perm:[2,3,0,1] row_mask:0xf bank_mask:0xf
	v_add_f32_dpp v8, v8, v8 row_half_mirror row_mask:0xf bank_mask:0xf
	v_add_f32_dpp v9, v9, v9 row_half_mirror row_mask:0xf bank_mask:0xf
	v_add_f32_dpp v10, v10, v10 row_half_mirror row_mask:0xf bank_mask:0xf
	v_add_f32_dpp v11, v11, v11 row_half_mirror row_mask:0xf bank_mask:0xf
	v_add_f32_dpp v8, v8, v8 row_mirror row_mask:0xf bank_mask:0xf
	v_add_f32_dpp v9, v9, v9 row_mirror row_mask:0xf bank_mask:0xf
	v_add_f32_dpp v10, v10, v10 row_mirror row_mask:0xf bank_mask:0xf
	v_add_f32_dpp v11, v11, v11 row_mirror row_mask:0xf bank_mask:0xf
	v_add_f32_dpp v8, v8, v8 row_bcast:15 row_mask:0xa bank_mask:0xf
	v_add_f32_dpp v9, v9, v9 row_bcast:15 row_mask:0xa bank_mask:0xf
	v_add_f32_dpp v10, v10, v10 row_bcast:15 row_mask:0xa bank_mask:0xf
	v_add_f32_dpp v11, v11, v11 row_bcast:15 row_mask:0xa bank_mask:0xf
	v_add_f32_dpp v8, v8, v8 row_bcast:31 row_mask:0xc bank_mask:0xf
	v_add_f32_dpp v9, v9, v9 row_bcast:31 row_mask:0xc bank_mask:0xf
	v_add_f32_dpp v10, v10, v10 row_bcast:31 row_mask:0xc bank_mask:0xf
	v_add_f32_dpp v11, v11, v11 row_bcast:31 row_mask:0xc bank_mask:0xf
	v_readlane_b32 s0, v8, 63
	v_readlane_b32 s1, v9, 63
	v_readlane_b32 s14, v10, 63
	v_readlane_b32 s15, v11, 63
	v_mov_b32_e32 v8, s0
	v_mov_b32_e32 v9, s1
	v_max_f32_e32 v8, 0x179abe15, v8
	v_max_f32_e32 v9, 0x179abe15, v9
	v_rsq_f32_e32 v8, v8
	v_rsq_f32_e32 v9, v9
	v_mul_f32_e32 v12, v249, v180
	v_mul_f32_e32 v250, v12, v181
	v_mul_f32_e32 v4, v4, v8
	v_mul_f32_e32 v5, v5, v9
	v_rcp_f32_e32 v8, v12
	v_rcp_f32_e32 v9, v250
	v_writelane_b32 v173, s14, 4
	v_writelane_b32 v173, s15, 5
	v_mul_f32_e32 v0, v188, v4
	v_mul_f32_e32 v1, v189, v5
	v_mul_f32_e32 v2, v249, v4
	v_mul_f32_e32 v0, v8, v0
	v_mul_f32_e32 v242, v8, v6
	v_mul_f32_e32 v1, v9, v1
	v_mul_f32_e32 v243, v9, v7
	v_mul_f32_e32 v244, v12, v5
	v_mul_f32_e32 v247, v153, v12
	v_mul_f32_e32 v248, v154, v250
	ds_write2st64_b32 v96, v12, v2 offset0:24 offset1:25
	ds_write2st64_b32 v96, v0, v242 offset0:26 offset1:27
	ds_write2st64_b32 v96, v247, v169 offset0:28 offset1:29
	ds_write2st64_b32 v96, v250, v244 offset0:30 offset1:31
	ds_write2st64_b32 v96, v1, v243 offset0:32 offset1:33
	ds_write2st64_b32 v96, v248, v170 offset0:34 offset1:35
	v_mul_f32_e32 v4, v26, v163
	v_mul_f32_e32 v5, v26, v164
	v_add_f32_e32 v6, -1.0, v190
	v_add_f32_e32 v7, -1.0, v191
	v_mul_f32_e32 v8, v4, v4
	v_mul_f32_e32 v9, v5, v5
	v_fma_f32 v6, v27, v6, 1.0
	v_fma_f32 v7, v27, v7, 1.0
	v_mul_f32_e32 v6, v163, v6
	v_mul_f32_e32 v7, v164, v7
	v_mul_f32_e32 v10, v155, v6
	v_mul_f32_e32 v11, v156, v7
	v_mul_f32_e32 v10, v29, v10
	v_mul_f32_e32 v11, v29, v11
	v_add_f32_dpp v8, v8, v8 quad_perm:[1,0,3,2] row_mask:0xf bank_mask:0xf
	v_add_f32_dpp v9, v9, v9 quad_perm:[1,0,3,2] row_mask:0xf bank_mask:0xf
	v_add_f32_dpp v10, v10, v10 quad_perm:[1,0,3,2] row_mask:0xf bank_mask:0xf
	v_add_f32_dpp v11, v11, v11 quad_perm:[1,0,3,2] row_mask:0xf bank_mask:0xf
	v_add_f32_dpp v8, v8, v8 quad_perm:[2,3,0,1] row_mask:0xf bank_mask:0xf
	v_add_f32_dpp v9, v9, v9 quad_perm:[2,3,0,1] row_mask:0xf bank_mask:0xf
	v_add_f32_dpp v10, v10, v10 quad_perm:[2,3,0,1] row_mask:0xf bank_mask:0xf
	v_add_f32_dpp v11, v11, v11 quad_perm:[2,3,0,1] row_mask:0xf bank_mask:0xf
	v_add_f32_dpp v8, v8, v8 row_half_mirror row_mask:0xf bank_mask:0xf
	v_add_f32_dpp v9, v9, v9 row_half_mirror row_mask:0xf bank_mask:0xf
	v_add_f32_dpp v10, v10, v10 row_half_mirror row_mask:0xf bank_mask:0xf
	v_add_f32_dpp v11, v11, v11 row_half_mirror row_mask:0xf bank_mask:0xf
	v_add_f32_dpp v8, v8, v8 row_mirror row_mask:0xf bank_mask:0xf
	v_add_f32_dpp v9, v9, v9 row_mirror row_mask:0xf bank_mask:0xf
	v_add_f32_dpp v10, v10, v10 row_mirror row_mask:0xf bank_mask:0xf
	v_add_f32_dpp v11, v11, v11 row_mirror row_mask:0xf bank_mask:0xf
	v_add_f32_dpp v8, v8, v8 row_bcast:15 row_mask:0xa bank_mask:0xf
	v_add_f32_dpp v9, v9, v9 row_bcast:15 row_mask:0xa bank_mask:0xf
	v_add_f32_dpp v10, v10, v10 row_bcast:15 row_mask:0xa bank_mask:0xf
	v_add_f32_dpp v11, v11, v11 row_bcast:15 row_mask:0xa bank_mask:0xf
	v_add_f32_dpp v8, v8, v8 row_bcast:31 row_mask:0xc bank_mask:0xf
	v_add_f32_dpp v9, v9, v9 row_bcast:31 row_mask:0xc bank_mask:0xf
	v_add_f32_dpp v10, v10, v10 row_bcast:31 row_mask:0xc bank_mask:0xf
	v_add_f32_dpp v11, v11, v11 row_bcast:31 row_mask:0xc bank_mask:0xf
	v_readlane_b32 s0, v8, 63
	v_readlane_b32 s1, v9, 63
	v_readlane_b32 s14, v10, 63
	v_readlane_b32 s15, v11, 63
	v_mov_b32_e32 v8, s0
	v_mov_b32_e32 v9, s1
	v_max_f32_e32 v8, 0x179abe15, v8
	v_max_f32_e32 v9, 0x179abe15, v9
	v_rsq_f32_e32 v8, v8
	v_rsq_f32_e32 v9, v9
	v_mul_f32_e32 v12, v250, v182
	v_mul_f32_e32 v249, v12, v183
	v_mul_f32_e32 v4, v4, v8
	v_mul_f32_e32 v5, v5, v9
	v_rcp_f32_e32 v8, v12
	v_rcp_f32_e32 v9, v249
	v_writelane_b32 v173, s14, 6
	v_writelane_b32 v173, s15, 7
	v_mul_f32_e32 v0, v190, v4
	v_mul_f32_e32 v1, v191, v5
	v_mul_f32_e32 v2, v250, v4
	v_mul_f32_e32 v0, v8, v0
	v_mul_f32_e32 v242, v8, v6
	v_mul_f32_e32 v1, v9, v1
	v_mul_f32_e32 v243, v9, v7
	v_mul_f32_e32 v244, v12, v5
	v_mul_f32_e32 v247, v155, v12
	v_mul_f32_e32 v248, v156, v249
	ds_write2st64_b32 v96, v12, v2 offset0:36 offset1:37
	ds_write2st64_b32 v96, v0, v242 offset0:38 offset1:39
	ds_write2st64_b32 v96, v247, v171 offset0:40 offset1:41
	ds_write2st64_b32 v96, v249, v244 offset0:42 offset1:43
	ds_write2st64_b32 v96, v1, v243 offset0:44 offset1:45
	ds_write2st64_b32 v96, v248, v172 offset0:46 offset1:47
	s_cmp_eq_u32 s62, 0
	s_cselect_b32 s0, 0, 7
	s_sub_u32 s0, s6, s0
	s_lshl_b32 s0, s0, 6
	s_add_u32 s16, s22, s0
	s_addc_u32 s17, s23, 0
	s_mov_b64 exec, 0xff
	global_store_dword v174, v173, s[16:17]
	s_mov_b64 exec, -1
	s_waitcnt lgkmcnt(0)
	s_barrier
	s_add_u32 s8, s8, 1
	s_cmp_lt_u32 s8, 0x90
	s_cbranch_scc1 .Lprep_group

; __global__ void __launch_bounds__(256, 2) fwd_megakernel(Params p) {
;   cg::grid_group grid = cg::this_grid();
;   __shared__ __attribute__((aligned(16))) unsigned char smem[SMEM_BYTES];
	.amdhsa_kernel _Z14fwd_megakernel6Params
		.amdhsa_group_segment_fixed_size 63520
		.amdhsa_private_segment_fixed_size 0
		.amdhsa_kernarg_size 664
		.amdhsa_user_sgpr_count 2
		.amdhsa_user_sgpr_dispatch_ptr 0
		.amdhsa_user_sgpr_queue_ptr 0
		.amdhsa_user_sgpr_kernarg_segment_ptr 1
		.amdhsa_user_sgpr_dispatch_id 0
		.amdhsa_user_sgpr_kernarg_preload_length 0
		.amdhsa_user_sgpr_kernarg_preload_offset 0
		.amdhsa_user_sgpr_private_segment_size 0
		.amdhsa_uses_dynamic_stack 0
		.amdhsa_enable_private_segment 0
		.amdhsa_system_sgpr_workgroup_id_x 1
		.amdhsa_system_sgpr_workgroup_id_y 0
		.amdhsa_system_sgpr_workgroup_id_z 0
		.amdhsa_system_sgpr_workgroup_info 0
		.amdhsa_system_vgpr_workitem_id 2
		.amdhsa_next_free_vgpr 256
		.amdhsa_next_free_sgpr 98
		.amdhsa_accum_offset 256
		.amdhsa_reserve_vcc 1
		.amdhsa_float_round_mode_32 0
		.amdhsa_float_round_mode_16_64 0
		.amdhsa_float_denorm_mode_32 3
		.amdhsa_float_denorm_mode_16_64 3
		.amdhsa_dx10_clamp 1
		.amdhsa_ieee_mode 1
		.amdhsa_fp16_overflow 0
		.amdhsa_tg_split 0
		.amdhsa_exception_fp_ieee_invalid_op 0
		.amdhsa_exception_fp_denorm_src 0
		.amdhsa_exception_fp_ieee_div_zero 0
		.amdhsa_exception_fp_ieee_overflow 0
		.amdhsa_exception_fp_ieee_underflow 0
		.amdhsa_exception_fp_ieee_inexact 0
		.amdhsa_exception_int_div_zero 0
	.end_amdhsa_kernel

; __global__ void __launch_bounds__(256, 2) fwd_megakernel(Params p) {
;   cg::grid_group grid = cg::this_grid();
;   __shared__ __attribute__((aligned(16))) unsigned char smem[SMEM_BYTES];
amdhsa.kernels:
  - .agpr_count:     0
    .args:
      - .offset:         0
        .size:           408
        .value_kind:     by_value
      - .offset:         408
        .size:           4
        .value_kind:     hidden_block_count_x
      - .offset:         412
        .size:           4
        .value_kind:     hidden_block_count_y
      - .offset:         416
        .size:           4
        .value_kind:     hidden_block_count_z
      - .offset:         420
        .size:           2
        .value_kind:     hidden_group_size_x
      - .offset:         422
        .size:           2
        .value_kind:     hidden_group_size_y
      - .offset:         424
        .size:           2
        .value_kind:     hidden_group_size_z
      - .offset:         426
        .size:           2
        .value_kind:     hidden_remainder_x
      - .offset:         428
        .size:           2
        .value_kind:     hidden_remainder_y
      - .offset:         430
        .size:           2
        .value_kind:     hidden_remainder_z
      - .offset:         448
        .size:           8
        .value_kind:     hidden_global_offset_x
      - .offset:         456
        .size:           8
        .value_kind:     hidden_global_offset_y
      - .offset:         464
        .size:           8
        .value_kind:     hidden_global_offset_z
      - .offset:         472
        .size:           2
        .value_kind:     hidden_grid_dims
      - .offset:         496
        .size:           8
        .value_kind:     hidden_multigrid_sync_arg
    .group_segment_fixed_size: 63520
    .kernarg_segment_align: 8
    .kernarg_segment_size: 664
    .language:       OpenCL C
    .language_version:
      - 2
      - 0
    .max_flat_workgroup_size: 256
    .name:           _Z14fwd_megakernel6Params
    .private_segment_fixed_size: 0
    .sgpr_count:     104
    .sgpr_spill_count: 125
    .symbol:         _Z14fwd_megakernel6Params.kd
    .uniform_work_group_size: 1
    .uses_dynamic_stack: false
    .vgpr_count:     256
    .vgpr_spill_count: 0
    .wavefront_size: 64
